# phase_mod GEMV loop software-pipelined 4 deep (16 loads in flight); attention max chains interleaved
# speedup vs baseline: 1.0081x; 1.0081x over previous
; DI void phase_mod(ArgsP a, int tb_, char* shm, int vcu, int G) {
;     ...
;     for (int it = vcu; it < 2 * 144; it += G) {
;         const int l = it / 144, n0 = (it % 144) * 64;
;         const float* w = a->in[I_WADA] + (size_t)l * D * (NMOD * D) + n0 + lane;
;         float s[9];
; #pragma unroll
;         for (int r = 0; r < 9; ++r) s[r] = 0.f;
;         const int kb = wave * 128;
; #pragma unroll 4
;         for (int k = 0; k < 128; ++k) { const float wv = w[(size_t)(kb + k) * (NMOD * D)];
; #pragma unroll
;             for (int r = 0; r < 9; ++r) s[r] += sc[r * D + kb + k] * wv; }
.LBB0_40:
	s_mul_hi_i32 s4, s19, 0x38e38e39
	s_lshr_b32 s5, s4, 31
	s_ashr_i32 s4, s4, 5
	s_add_i32 s14, s4, s5
	s_mul_i32 s4, s14, 0x90
	s_sub_i32 s4, s19, s4
	s_lshl_b32 s4, s4, 6
	s_ashr_i32 s5, s4, 31
	s_mul_i32 s9, s14, 0x2400000
	s_lshl_b64 s[6:7], s[4:5], 2
	s_mul_hi_i32 s8, s14, 0x2400000
	s_add_u32 s4, s9, s6
	s_addc_u32 s5, s8, s7
	v_mov_b32_e32 v6, 0
	v_lshl_add_u64 v[4:5], v[2:3], 0, s[4:5]
	s_mov_b64 s[8:9], 0
	v_mov_b32_e32 v15, v1
	v_mov_b32_e32 v7, v6
	v_mov_b32_e32 v8, v6
	v_mov_b32_e32 v9, v6
	v_mov_b32_e32 v10, v6
	v_mov_b32_e32 v11, v6
	v_mov_b32_e32 v12, v6
	v_mov_b32_e32 v13, v6
	v_mov_b32_e32 v16, v6
	v_lshl_add_u64 v[18:19], v[4:5], 0, s[8:9]
	v_add_co_u32_e64 v20, s[4:5], s59, v18
	global_load_dword v54, v[18:19], off
	s_nop 0
	v_addc_co_u32_e64 v21, s[4:5], 0, v19, s[4:5]
	v_add_co_u32_e64 v22, s[4:5], s53, v18
	s_add_u32 s8, s8, 0x24000
	s_nop 0
	v_addc_co_u32_e64 v23, s[4:5], 0, v19, s[4:5]
	v_add_co_u32_e64 v18, s[4:5], s56, v18
	s_addc_u32 s9, s9, 0
	s_nop 0
	v_addc_co_u32_e64 v19, s[4:5], 0, v19, s[4:5]
	global_load_dword v56, v[20:21], off
	global_load_dword v58, v[22:23], off
	global_load_dword v60, v[18:19], off
	v_lshl_add_u64 v[18:19], v[4:5], 0, s[8:9]
	v_add_co_u32_e64 v20, s[4:5], s59, v18
	global_load_dword v70, v[18:19], off
	s_nop 0
	v_addc_co_u32_e64 v21, s[4:5], 0, v19, s[4:5]
	v_add_co_u32_e64 v22, s[4:5], s53, v18
	s_add_u32 s8, s8, 0x24000
	s_nop 0
	v_addc_co_u32_e64 v23, s[4:5], 0, v19, s[4:5]
	v_add_co_u32_e64 v18, s[4:5], s56, v18
	s_addc_u32 s9, s9, 0
	s_nop 0
	v_addc_co_u32_e64 v19, s[4:5], 0, v19, s[4:5]
	global_load_dword v72, v[20:21], off
	global_load_dword v74, v[22:23], off
	global_load_dword v76, v[18:19], off
	v_lshl_add_u64 v[18:19], v[4:5], 0, s[8:9]
	v_add_co_u32_e64 v20, s[4:5], s59, v18
	global_load_dword v78, v[18:19], off
	s_nop 0
	v_addc_co_u32_e64 v21, s[4:5], 0, v19, s[4:5]
	v_add_co_u32_e64 v22, s[4:5], s53, v18
	s_add_u32 s8, s8, 0x24000
	s_nop 0
	v_addc_co_u32_e64 v23, s[4:5], 0, v19, s[4:5]
	v_add_co_u32_e64 v18, s[4:5], s56, v18
	s_addc_u32 s9, s9, 0
	s_nop 0
	v_addc_co_u32_e64 v19, s[4:5], 0, v19, s[4:5]
	global_load_dword v80, v[20:21], off
	global_load_dword v82, v[22:23], off
	global_load_dword v84, v[18:19], off
.LBB0_41:
	s_min_u32 s22, s8, 0x45c000
	s_mov_b32 s23, 0
	v_lshl_add_u64 v[18:19], v[4:5], 0, s[22:23]
	v_add_co_u32_e64 v20, s[4:5], s59, v18
	global_load_dword v86, v[18:19], off
	s_nop 0
	v_addc_co_u32_e64 v21, s[4:5], 0, v19, s[4:5]
	v_add_co_u32_e64 v22, s[4:5], s53, v18
	s_add_u32 s8, s8, 0x24000
	s_nop 0
	v_addc_co_u32_e64 v23, s[4:5], 0, v19, s[4:5]
	v_add_co_u32_e64 v18, s[4:5], s56, v18
	s_addc_u32 s9, s9, 0
	s_nop 0
	v_addc_co_u32_e64 v19, s[4:5], 0, v19, s[4:5]
	global_load_dword v88, v[20:21], off
	global_load_dword v90, v[22:23], off
	global_load_dword v92, v[18:19], off
	ds_read_b128 v[18:21], v15 offset:4096
	ds_read_b128 v[22:25], v15 offset:8192
	ds_read_b128 v[26:29], v15 offset:12288
	ds_read_b128 v[30:33], v15 offset:16384
	ds_read_b128 v[34:37], v15 offset:20480
	ds_read_b128 v[38:41], v15 offset:24576
	ds_read_b128 v[42:45], v15 offset:28672
	ds_read_b128 v[46:49], v15
	ds_read_b128 v[50:53], v15 offset:32768
	s_waitcnt lgkmcnt(0)
	v_mov_b32_e32 v63, v18
	s_waitcnt lgkmcnt(7)
	v_mov_b32_e32 v64, v22
	s_waitcnt lgkmcnt(6)
	v_mov_b32_e32 v65, v26
	s_waitcnt lgkmcnt(1)
	v_mov_b32_e32 v62, v46
	v_mov_b32_e32 v66, v30
	v_mov_b32_e32 v67, v34
	v_mov_b32_e32 v68, v38
	v_mov_b32_e32 v69, v42
	v_mov_b32_e32 v18, v47
	v_mov_b32_e32 v26, v23
	v_mov_b32_e32 v34, v31
	v_mov_b32_e32 v42, v39
	v_mov_b32_e32 v22, v48
	v_mov_b32_e32 v23, v20
	v_mov_b32_e32 v30, v24
	v_mov_b32_e32 v31, v28
	v_mov_b32_e32 v38, v32
	v_mov_b32_e32 v39, v36
	v_mov_b32_e32 v46, v40
	v_mov_b32_e32 v47, v44
	v_mov_b32_e32 v20, v49
	v_mov_b32_e32 v28, v25
	v_mov_b32_e32 v36, v33
	v_mov_b32_e32 v44, v41
	v_add_u32_e32 v15, 16, v15
	s_waitcnt vmcnt(12)
	v_pk_fma_f32 v[6:7], v[54:55], v[62:63], v[6:7] op_sel_hi:[0,1,1]
	v_pk_fma_f32 v[8:9], v[54:55], v[64:65], v[8:9] op_sel_hi:[0,1,1]
	v_pk_fma_f32 v[10:11], v[54:55], v[66:67], v[10:11] op_sel_hi:[0,1,1]
	v_pk_fma_f32 v[12:13], v[54:55], v[68:69], v[12:13] op_sel_hi:[0,1,1]
	s_waitcnt lgkmcnt(0)
	v_fmac_f32_e32 v16, v54, v50
	v_pk_fma_f32 v[6:7], v[56:57], v[18:19], v[6:7] op_sel_hi:[0,1,1]
	v_pk_fma_f32 v[8:9], v[56:57], v[26:27], v[8:9] op_sel_hi:[0,1,1]
	v_pk_fma_f32 v[10:11], v[56:57], v[34:35], v[10:11] op_sel_hi:[0,1,1]
	v_pk_fma_f32 v[12:13], v[56:57], v[42:43], v[12:13] op_sel_hi:[0,1,1]
	v_fmac_f32_e32 v16, v56, v51
	v_pk_fma_f32 v[6:7], v[58:59], v[22:23], v[6:7] op_sel_hi:[0,1,1]
	v_pk_fma_f32 v[8:9], v[58:59], v[30:31], v[8:9] op_sel_hi:[0,1,1]
	v_pk_fma_f32 v[10:11], v[58:59], v[38:39], v[10:11] op_sel_hi:[0,1,1]
	v_pk_fma_f32 v[12:13], v[58:59], v[46:47], v[12:13] op_sel_hi:[0,1,1]
	v_fmac_f32_e32 v16, v58, v52
	v_pk_fma_f32 v[6:7], v[60:61], v[20:21], v[6:7] op_sel_hi:[0,1,1]
	v_pk_fma_f32 v[8:9], v[60:61], v[28:29], v[8:9] op_sel_hi:[0,1,1]
	v_pk_fma_f32 v[10:11], v[60:61], v[36:37], v[10:11] op_sel_hi:[0,1,1]
	v_pk_fma_f32 v[12:13], v[60:61], v[44:45], v[12:13] op_sel_hi:[0,1,1]
	v_fmac_f32_e32 v16, v60, v53
	s_min_u32 s22, s8, 0x45c000
	s_mov_b32 s23, 0
	v_lshl_add_u64 v[18:19], v[4:5], 0, s[22:23]
	v_add_co_u32_e64 v20, s[4:5], s59, v18
	global_load_dword v54, v[18:19], off
	s_nop 0
	v_addc_co_u32_e64 v21, s[4:5], 0, v19, s[4:5]
	v_add_co_u32_e64 v22, s[4:5], s53, v18
	s_add_u32 s8, s8, 0x24000
	s_nop 0
	v_addc_co_u32_e64 v23, s[4:5], 0, v19, s[4:5]
	v_add_co_u32_e64 v18, s[4:5], s56, v18
	s_addc_u32 s9, s9, 0
	s_nop 0
	v_addc_co_u32_e64 v19, s[4:5], 0, v19, s[4:5]
	global_load_dword v56, v[20:21], off
	global_load_dword v58, v[22:23], off
	global_load_dword v60, v[18:19], off
	ds_read_b128 v[18:21], v15 offset:4096
	ds_read_b128 v[22:25], v15 offset:8192
	ds_read_b128 v[26:29], v15 offset:12288
	ds_read_b128 v[30:33], v15 offset:16384
	ds_read_b128 v[34:37], v15 offset:20480
	ds_read_b128 v[38:41], v15 offset:24576
	ds_read_b128 v[42:45], v15 offset:28672
	ds_read_b128 v[46:49], v15
	ds_read_b128 v[50:53], v15 offset:32768
	s_waitcnt lgkmcnt(0)
; DI void phase_mod(ArgsP a, int tb_, char* shm, int vcu, int G) {
;     ...
; #pragma unroll 4
;         for (int k = 0; k < 128; ++k) { const float wv = w[(size_t)(kb + k) * (NMOD * D)];
; #pragma unroll
;             for (int r = 0; r < 9; ++r) s[r] += sc[r * D + kb + k] * wv; }
	v_mov_b32_e32 v63, v18
	s_waitcnt lgkmcnt(7)
	v_mov_b32_e32 v64, v22
	s_waitcnt lgkmcnt(6)
	v_mov_b32_e32 v65, v26
	s_waitcnt lgkmcnt(1)
	v_mov_b32_e32 v62, v46
	v_mov_b32_e32 v66, v30
	v_mov_b32_e32 v67, v34
	v_mov_b32_e32 v68, v38
	v_mov_b32_e32 v69, v42
	v_mov_b32_e32 v18, v47
	v_mov_b32_e32 v26, v23
	v_mov_b32_e32 v34, v31
	v_mov_b32_e32 v42, v39
	v_mov_b32_e32 v22, v48
	v_mov_b32_e32 v23, v20
	v_mov_b32_e32 v30, v24
	v_mov_b32_e32 v31, v28
	v_mov_b32_e32 v38, v32
	v_mov_b32_e32 v39, v36
	v_mov_b32_e32 v46, v40
	v_mov_b32_e32 v47, v44
	v_mov_b32_e32 v20, v49
	v_mov_b32_e32 v28, v25
	v_mov_b32_e32 v36, v33
	v_mov_b32_e32 v44, v41
	v_add_u32_e32 v15, 16, v15
	s_waitcnt vmcnt(12)
	v_pk_fma_f32 v[6:7], v[70:71], v[62:63], v[6:7] op_sel_hi:[0,1,1]
	v_pk_fma_f32 v[8:9], v[70:71], v[64:65], v[8:9] op_sel_hi:[0,1,1]
	v_pk_fma_f32 v[10:11], v[70:71], v[66:67], v[10:11] op_sel_hi:[0,1,1]
	v_pk_fma_f32 v[12:13], v[70:71], v[68:69], v[12:13] op_sel_hi:[0,1,1]
	s_waitcnt lgkmcnt(0)
	v_fmac_f32_e32 v16, v70, v50
	v_pk_fma_f32 v[6:7], v[72:73], v[18:19], v[6:7] op_sel_hi:[0,1,1]
	v_pk_fma_f32 v[8:9], v[72:73], v[26:27], v[8:9] op_sel_hi:[0,1,1]
	v_pk_fma_f32 v[10:11], v[72:73], v[34:35], v[10:11] op_sel_hi:[0,1,1]
	v_pk_fma_f32 v[12:13], v[72:73], v[42:43], v[12:13] op_sel_hi:[0,1,1]
	v_fmac_f32_e32 v16, v72, v51
	v_pk_fma_f32 v[6:7], v[74:75], v[22:23], v[6:7] op_sel_hi:[0,1,1]
	v_pk_fma_f32 v[8:9], v[74:75], v[30:31], v[8:9] op_sel_hi:[0,1,1]
	v_pk_fma_f32 v[10:11], v[74:75], v[38:39], v[10:11] op_sel_hi:[0,1,1]
	v_pk_fma_f32 v[12:13], v[74:75], v[46:47], v[12:13] op_sel_hi:[0,1,1]
	v_fmac_f32_e32 v16, v74, v52
	v_pk_fma_f32 v[6:7], v[76:77], v[20:21], v[6:7] op_sel_hi:[0,1,1]
	v_pk_fma_f32 v[8:9], v[76:77], v[28:29], v[8:9] op_sel_hi:[0,1,1]
	v_pk_fma_f32 v[10:11], v[76:77], v[36:37], v[10:11] op_sel_hi:[0,1,1]
	v_pk_fma_f32 v[12:13], v[76:77], v[44:45], v[12:13] op_sel_hi:[0,1,1]
	v_fmac_f32_e32 v16, v76, v53
	s_min_u32 s22, s8, 0x45c000
	s_mov_b32 s23, 0
	v_lshl_add_u64 v[18:19], v[4:5], 0, s[22:23]
	v_add_co_u32_e64 v20, s[4:5], s59, v18
	global_load_dword v70, v[18:19], off
	s_nop 0
	v_addc_co_u32_e64 v21, s[4:5], 0, v19, s[4:5]
	v_add_co_u32_e64 v22, s[4:5], s53, v18
	s_add_u32 s8, s8, 0x24000
	s_nop 0
	v_addc_co_u32_e64 v23, s[4:5], 0, v19, s[4:5]
	v_add_co_u32_e64 v18, s[4:5], s56, v18
	s_addc_u32 s9, s9, 0
	s_nop 0
	v_addc_co_u32_e64 v19, s[4:5], 0, v19, s[4:5]
	global_load_dword v72, v[20:21], off
	global_load_dword v74, v[22:23], off
	global_load_dword v76, v[18:19], off
	ds_read_b128 v[18:21], v15 offset:4096
	ds_read_b128 v[22:25], v15 offset:8192
	ds_read_b128 v[26:29], v15 offset:12288
	ds_read_b128 v[30:33], v15 offset:16384
	ds_read_b128 v[34:37], v15 offset:20480
	ds_read_b128 v[38:41], v15 offset:24576
	ds_read_b128 v[42:45], v15 offset:28672
	ds_read_b128 v[46:49], v15
	ds_read_b128 v[50:53], v15 offset:32768
	s_waitcnt lgkmcnt(0)
	v_mov_b32_e32 v63, v18
	s_waitcnt lgkmcnt(7)
	v_mov_b32_e32 v64, v22
	s_waitcnt lgkmcnt(6)
	v_mov_b32_e32 v65, v26
	s_waitcnt lgkmcnt(1)
	v_mov_b32_e32 v62, v46
	v_mov_b32_e32 v66, v30
	v_mov_b32_e32 v67, v34
	v_mov_b32_e32 v68, v38
	v_mov_b32_e32 v69, v42
	v_mov_b32_e32 v18, v47
	v_mov_b32_e32 v26, v23
	v_mov_b32_e32 v34, v31
	v_mov_b32_e32 v42, v39
	v_mov_b32_e32 v22, v48
	v_mov_b32_e32 v23, v20
	v_mov_b32_e32 v30, v24
	v_mov_b32_e32 v31, v28
	v_mov_b32_e32 v38, v32
	v_mov_b32_e32 v39, v36
	v_mov_b32_e32 v46, v40
	v_mov_b32_e32 v47, v44
	v_mov_b32_e32 v20, v49
	v_mov_b32_e32 v28, v25
	v_mov_b32_e32 v36, v33
	v_mov_b32_e32 v44, v41
	v_add_u32_e32 v15, 16, v15
	s_waitcnt vmcnt(12)
	v_pk_fma_f32 v[6:7], v[78:79], v[62:63], v[6:7] op_sel_hi:[0,1,1]
	v_pk_fma_f32 v[8:9], v[78:79], v[64:65], v[8:9] op_sel_hi:[0,1,1]
	v_pk_fma_f32 v[10:11], v[78:79], v[66:67], v[10:11] op_sel_hi:[0,1,1]
	v_pk_fma_f32 v[12:13], v[78:79], v[68:69], v[12:13] op_sel_hi:[0,1,1]
	s_waitcnt lgkmcnt(0)
; DI void phase_mod(ArgsP a, int tb_, char* shm, int vcu, int G) {
;     ...
;         const int kb = wave * 128;
; #pragma unroll 4
;         for (int k = 0; k < 128; ++k) { const float wv = w[(size_t)(kb + k) * (NMOD * D)];
; #pragma unroll
;             for (int r = 0; r < 9; ++r) s[r] += sc[r * D + kb + k] * wv; }
; #pragma unroll
;         for (int r = 0; r < 9; ++r) part[(wave * 9 + r) * 64 + lane] = s[r];
;         __syncthreads();
;         for (int i = tid; i < 9 * 64; i += NTHR) { const int r = i / 64, n = i % 64; float t = a->in[I_BADA][(size_t)l * (NMOD * D) + n0 + n];
; #pragma unroll
;             for (int w8 = 0; w8 < 8; ++w8) t += part[(w8 * 9 + r) * 64 + n];
;             mod[((size_t)l * 9 + r) * (NMOD * D) + n0 + n] = t; }
	v_fmac_f32_e32 v16, v78, v50
	v_pk_fma_f32 v[6:7], v[80:81], v[18:19], v[6:7] op_sel_hi:[0,1,1]
	v_pk_fma_f32 v[8:9], v[80:81], v[26:27], v[8:9] op_sel_hi:[0,1,1]
	v_pk_fma_f32 v[10:11], v[80:81], v[34:35], v[10:11] op_sel_hi:[0,1,1]
	v_pk_fma_f32 v[12:13], v[80:81], v[42:43], v[12:13] op_sel_hi:[0,1,1]
	v_fmac_f32_e32 v16, v80, v51
	v_pk_fma_f32 v[6:7], v[82:83], v[22:23], v[6:7] op_sel_hi:[0,1,1]
	v_pk_fma_f32 v[8:9], v[82:83], v[30:31], v[8:9] op_sel_hi:[0,1,1]
	v_pk_fma_f32 v[10:11], v[82:83], v[38:39], v[10:11] op_sel_hi:[0,1,1]
	v_pk_fma_f32 v[12:13], v[82:83], v[46:47], v[12:13] op_sel_hi:[0,1,1]
	v_fmac_f32_e32 v16, v82, v52
	v_pk_fma_f32 v[6:7], v[84:85], v[20:21], v[6:7] op_sel_hi:[0,1,1]
	v_pk_fma_f32 v[8:9], v[84:85], v[28:29], v[8:9] op_sel_hi:[0,1,1]
	v_pk_fma_f32 v[10:11], v[84:85], v[36:37], v[10:11] op_sel_hi:[0,1,1]
	v_pk_fma_f32 v[12:13], v[84:85], v[44:45], v[12:13] op_sel_hi:[0,1,1]
	v_fmac_f32_e32 v16, v84, v53
	s_min_u32 s22, s8, 0x45c000
	s_mov_b32 s23, 0
	v_lshl_add_u64 v[18:19], v[4:5], 0, s[22:23]
	v_add_co_u32_e64 v20, s[4:5], s59, v18
	global_load_dword v78, v[18:19], off
	s_nop 0
	v_addc_co_u32_e64 v21, s[4:5], 0, v19, s[4:5]
	v_add_co_u32_e64 v22, s[4:5], s53, v18
	s_add_u32 s8, s8, 0x24000
	s_nop 0
	v_addc_co_u32_e64 v23, s[4:5], 0, v19, s[4:5]
	v_add_co_u32_e64 v18, s[4:5], s56, v18
	s_addc_u32 s9, s9, 0
	s_nop 0
	v_addc_co_u32_e64 v19, s[4:5], 0, v19, s[4:5]
	global_load_dword v80, v[20:21], off
	global_load_dword v82, v[22:23], off
	global_load_dword v84, v[18:19], off
	ds_read_b128 v[18:21], v15 offset:4096
	ds_read_b128 v[22:25], v15 offset:8192
	ds_read_b128 v[26:29], v15 offset:12288
	ds_read_b128 v[30:33], v15 offset:16384
	ds_read_b128 v[34:37], v15 offset:20480
	ds_read_b128 v[38:41], v15 offset:24576
	ds_read_b128 v[42:45], v15 offset:28672
	ds_read_b128 v[46:49], v15
	ds_read_b128 v[50:53], v15 offset:32768
	s_waitcnt lgkmcnt(0)
	v_mov_b32_e32 v63, v18
	s_waitcnt lgkmcnt(7)
	v_mov_b32_e32 v64, v22
	s_waitcnt lgkmcnt(6)
	v_mov_b32_e32 v65, v26
	s_waitcnt lgkmcnt(1)
	v_mov_b32_e32 v62, v46
	v_mov_b32_e32 v66, v30
	v_mov_b32_e32 v67, v34
	v_mov_b32_e32 v68, v38
	v_mov_b32_e32 v69, v42
	v_mov_b32_e32 v18, v47
	v_mov_b32_e32 v26, v23
	v_mov_b32_e32 v34, v31
	v_mov_b32_e32 v42, v39
	v_mov_b32_e32 v22, v48
	v_mov_b32_e32 v23, v20
	v_mov_b32_e32 v30, v24
	v_mov_b32_e32 v31, v28
	v_mov_b32_e32 v38, v32
	v_mov_b32_e32 v39, v36
	v_mov_b32_e32 v46, v40
	v_mov_b32_e32 v47, v44
	v_mov_b32_e32 v20, v49
	v_mov_b32_e32 v28, v25
	v_mov_b32_e32 v36, v33
	v_mov_b32_e32 v44, v41
	v_add_u32_e32 v15, 16, v15
	s_waitcnt vmcnt(12)
	v_pk_fma_f32 v[6:7], v[86:87], v[62:63], v[6:7] op_sel_hi:[0,1,1]
	v_pk_fma_f32 v[8:9], v[86:87], v[64:65], v[8:9] op_sel_hi:[0,1,1]
	v_pk_fma_f32 v[10:11], v[86:87], v[66:67], v[10:11] op_sel_hi:[0,1,1]
	v_pk_fma_f32 v[12:13], v[86:87], v[68:69], v[12:13] op_sel_hi:[0,1,1]
	s_waitcnt lgkmcnt(0)
	v_fmac_f32_e32 v16, v86, v50
	v_pk_fma_f32 v[6:7], v[88:89], v[18:19], v[6:7] op_sel_hi:[0,1,1]
	v_pk_fma_f32 v[8:9], v[88:89], v[26:27], v[8:9] op_sel_hi:[0,1,1]
	v_pk_fma_f32 v[10:11], v[88:89], v[34:35], v[10:11] op_sel_hi:[0,1,1]
	v_pk_fma_f32 v[12:13], v[88:89], v[42:43], v[12:13] op_sel_hi:[0,1,1]
	v_fmac_f32_e32 v16, v88, v51
	v_pk_fma_f32 v[6:7], v[90:91], v[22:23], v[6:7] op_sel_hi:[0,1,1]
	v_pk_fma_f32 v[8:9], v[90:91], v[30:31], v[8:9] op_sel_hi:[0,1,1]
	v_pk_fma_f32 v[10:11], v[90:91], v[38:39], v[10:11] op_sel_hi:[0,1,1]
	v_pk_fma_f32 v[12:13], v[90:91], v[46:47], v[12:13] op_sel_hi:[0,1,1]
	v_fmac_f32_e32 v16, v90, v52
	v_pk_fma_f32 v[6:7], v[92:93], v[20:21], v[6:7] op_sel_hi:[0,1,1]
	v_pk_fma_f32 v[8:9], v[92:93], v[28:29], v[8:9] op_sel_hi:[0,1,1]
	v_pk_fma_f32 v[10:11], v[92:93], v[36:37], v[10:11] op_sel_hi:[0,1,1]
	v_pk_fma_f32 v[12:13], v[92:93], v[44:45], v[12:13] op_sel_hi:[0,1,1]
	v_fmac_f32_e32 v16, v92, v53
	s_cmp_eq_u32 s8, 0x4ec000
	s_cbranch_scc0 .LBB0_41
	s_waitcnt vmcnt(0)
	ds_write2st64_b32 v14, v6, v7 offset0:144 offset1:145
	ds_write2st64_b32 v14, v8, v9 offset0:146 offset1:147
	ds_write2st64_b32 v14, v10, v11 offset0:148 offset1:149
	ds_write2st64_b32 v14, v12, v13 offset0:150 offset1:151
	ds_write_b32 v14, v16 offset:38912
	s_waitcnt lgkmcnt(0)
	s_barrier
	s_and_saveexec_b64 s[8:9], vcc
	s_cbranch_execz .LBB0_39
	s_load_dwordx2 s[4:5], s[10:11], 0x28
	s_add_u32 s12, s2, s6
	s_mul_i32 s16, s14, 0x9000
	s_addc_u32 s13, s18, s7
	s_mul_hi_i32 s15, s14, 0x9000
	s_waitcnt lgkmcnt(0)
	s_add_u32 s4, s4, s16
	s_addc_u32 s5, s5, s15
	s_add_u32 s6, s4, s6
	s_addc_u32 s7, s5, s7
	s_add_i32 s4, 0, 0x9000
	s_mul_hi_i32 s15, s14, 9
	s_mul_i32 s14, s14, 9
	v_lshl_add_u32 v4, v0, 2, s4
	s_mov_b64 s[16:17], 0
	v_mov_b32_e32 v5, v0

.Lat_loop:
	s_andn2_b64 vcc, exec, s[18:19]
	s_cbranch_vccnz .Lat_val_skip
	v_max3_f32 v211, v96, v97, v112
	v_max3_f32 v212, v64, v65, v80
	v_max3_f32 v211, v211, v113, v98
	v_max3_f32 v212, v212, v81, v66
	v_max3_f32 v211, v211, v98, v99
	v_max3_f32 v212, v212, v66, v67
	v_max3_f32 v211, v211, v114, v115
	v_max3_f32 v212, v212, v82, v83
	v_max3_f32 v211, v211, v100, v101
	v_max3_f32 v212, v212, v68, v69
	v_max3_f32 v211, v211, v116, v117
	v_max3_f32 v212, v212, v84, v85
	v_max3_f32 v211, v211, v102, v103
	v_max3_f32 v212, v212, v70, v71
	v_max3_f32 v211, v211, v118, v119
	v_max3_f32 v212, v212, v86, v87
	v_max3_f32 v211, v211, v104, v105
	v_max3_f32 v212, v212, v72, v73
	v_max3_f32 v211, v211, v120, v121
	v_max3_f32 v212, v212, v88, v89
	v_max3_f32 v211, v211, v106, v107
	v_max3_f32 v212, v212, v74, v75
	v_max3_f32 v211, v211, v122, v123
	v_max3_f32 v212, v212, v90, v91
	v_max3_f32 v211, v211, v108, v109
	v_max3_f32 v212, v212, v76, v77
	v_max3_f32 v211, v211, v124, v125
	v_max3_f32 v212, v212, v92, v93
	v_max3_f32 v211, v211, v110, v111
	v_max3_f32 v212, v212, v78, v79
	v_max3_f32 v211, v211, v126, v127
	v_max3_f32 v212, v212, v94, v95
	ds_bpermute_b32 v215, v202, v211
	ds_bpermute_b32 v216, v202, v212
	v_max_f32_e32 v211, v211, v211
	v_max_f32_e32 v212, v212, v212
	v_add_f32_e32 v217, 0x41000000, v214
	v_add_f32_e32 v218, 0x41000000, v213
	s_waitcnt lgkmcnt(0)
	v_max_f32_e32 v215, v215, v215
	v_max_f32_e32 v216, v216, v216
	v_max_f32_e32 v211, v211, v215
	v_max_f32_e32 v212, v212, v216
	v_cmp_gt_f32_e32 vcc, v211, v217
	v_cmp_gt_f32_e64 s[38:39], v212, v218
	s_nop 1
	s_or_b64 s[20:21], vcc, s[38:39]
	s_cmp_eq_u64 s[20:21], 0
	s_cbranch_scc1 .Lat_no_rs_both
	s_cmp_eq_u64 vcc, 0
	s_cbranch_scc1 .Lat_no_rs_a
	v_max_f32_e32 v211, v211, v211
	v_max_f32_e32 v242, v214, v214
	v_max_f32_e32 v211, v242, v211
	v_sub_f32_e32 v242, v214, v211
	v_exp_f32_e32 v242, v242
	s_and_saveexec_b64 s[20:21], s[6:7]
	ds_write_b32 v198, v242 offset:44032
	s_or_b64 exec, exec, s[20:21]
	v_mul_f32_e32 v203, v203, v242
	s_waitcnt lgkmcnt(0)
	v_add_u32_e32 v242, s33, v188
	ds_read_b128 v[214:217], v242 offset:44032
	ds_read_b128 v[218:221], v242 offset:44064
	ds_read_b128 v[222:225], v242 offset:44096
	ds_read_b128 v[226:229], v242 offset:44128
	s_waitcnt lgkmcnt(3)
	v_pk_mul_f32 v[34:35], v[34:35], v[216:217]
	s_waitcnt lgkmcnt(2)
	v_pk_mul_f32 v[36:37], v[36:37], v[218:219]
	s_waitcnt lgkmcnt(1)
	v_pk_mul_f32 v[40:41], v[40:41], v[222:223]
	s_waitcnt lgkmcnt(0)
	v_pk_mul_f32 v[44:45], v[44:45], v[226:227]
	v_pk_mul_f32 v[46:47], v[46:47], v[228:229]
	v_pk_mul_f32 v[42:43], v[42:43], v[224:225]
	v_pk_mul_f32 v[38:39], v[38:39], v[220:221]
	v_pk_mul_f32 v[32:33], v[32:33], v[214:215]
	v_pk_mul_f32 v[60:61], v[60:61], v[226:227]
	v_pk_mul_f32 v[56:57], v[56:57], v[222:223]
	v_pk_mul_f32 v[52:53], v[52:53], v[218:219]
	v_pk_mul_f32 v[62:63], v[62:63], v[228:229]
	v_pk_mul_f32 v[58:59], v[58:59], v[224:225]
	v_pk_mul_f32 v[54:55], v[54:55], v[220:221]
	v_pk_mul_f32 v[50:51], v[50:51], v[216:217]
	v_pk_mul_f32 v[48:49], v[48:49], v[214:215]
	s_branch .Lat_chk_b

.Lat_chk_b:
	s_cmp_eq_u64 s[38:39], 0
	s_cbranch_scc1 .Lat_no_rs_b
	v_max_f32_e32 v212, v212, v212
	v_max_f32_e32 v214, v213, v213
	v_max_f32_e32 v212, v214, v212
	v_sub_f32_e32 v213, v213, v212
	v_exp_f32_e32 v213, v213
	s_and_saveexec_b64 s[20:21], s[6:7]
	ds_write_b32 v198, v213 offset:44032
	s_or_b64 exec, exec, s[20:21]
	v_mul_f32_e32 v199, v199, v213
	s_waitcnt lgkmcnt(0)
	v_add_u32_e32 v213, s33, v188
	ds_read_b128 v[214:217], v213 offset:44032
	ds_read_b128 v[218:221], v213 offset:44064
	ds_read_b128 v[222:225], v213 offset:44096
	ds_read_b128 v[226:229], v213 offset:44128
	s_waitcnt lgkmcnt(3)
	v_pk_mul_f32 v[18:19], v[18:19], v[216:217]
	s_waitcnt lgkmcnt(2)
	v_pk_mul_f32 v[20:21], v[20:21], v[218:219]
	s_waitcnt lgkmcnt(1)
	v_pk_mul_f32 v[24:25], v[24:25], v[222:223]
	s_waitcnt lgkmcnt(0)
	v_pk_mul_f32 v[28:29], v[28:29], v[226:227]
	v_pk_mul_f32 v[30:31], v[30:31], v[228:229]
	v_pk_mul_f32 v[26:27], v[26:27], v[224:225]
	v_pk_mul_f32 v[22:23], v[22:23], v[220:221]
	v_pk_mul_f32 v[16:17], v[16:17], v[214:215]
	v_pk_mul_f32 v[12:13], v[12:13], v[226:227]
	v_pk_mul_f32 v[8:9], v[8:9], v[222:223]
	v_pk_mul_f32 v[4:5], v[4:5], v[218:219]
	v_pk_mul_f32 v[14:15], v[14:15], v[228:229]
	v_pk_mul_f32 v[10:11], v[10:11], v[224:225]
	v_pk_mul_f32 v[6:7], v[6:7], v[220:221]
	v_pk_mul_f32 v[2:3], v[2:3], v[216:217]
	v_pk_mul_f32 v[0:1], v[0:1], v[214:215]
	s_branch .Lat_exps
.Lat_no_rs_b:
	v_mov_b32_e32 v212, v213
	s_branch .Lat_exps
.Lat_no_rs_both:
	v_mov_b32_e32 v211, v214
	v_mov_b32_e32 v212, v213
